# NSA step loops: K/V tile LDS-DMA issue uses SGPR base + 32-bit lane offset (4 v_lshl_add_u64 per tile removed), 4th load issued inside each path
# speedup vs baseline: 1.0166x; 1.0005x over previous
; #define LAS __attribute__((address_space(3)))
; DI void glds16(const char* g, LAS unsigned char* l) { __builtin_amdgcn_global_load_lds((const unsigned*)g, (LAS unsigned*)l, 16, 0, 0); }
; DI void dma_kv128(LAS unsigned char* stage, unsigned ldsw, const char* K, const char* V, unsigned voff, long ldb) {
;   glds16(K + (size_t)voff, stage + ldsw); glds16(K + 32 * ldb + (size_t)voff, stage + ldsw + 8192);
;   glds16(V + (size_t)voff, stage + 16384 + ldsw); glds16(V + 32 * ldb + (size_t)voff, stage + 16384 + ldsw + 8192);
; }
.LBB0_603:
	s_cmp_ge_i32 s23, s14
	s_cbranch_scc0 .LBB0_605
	s_mul_i32 s5, s7, 0x3000
	s_mul_hi_i32 s4, s7, 0x3000
	s_add_u32 s28, s61, s5
	s_addc_u32 s29, s3, s4
	s_add_u32 s4, s28, s17
	s_addc_u32 s5, s29, 0
	s_add_u32 s28, s28, s18
	s_addc_u32 s29, s29, 0
	s_add_i32 s101, s8, s60
	s_mov_b32 m0, s101
	s_nop 0
	global_load_lds_dwordx4 v206, s[4:5]
	s_add_u32 s98, s4, s86
	s_addc_u32 s99, s5, s87
	s_add_i32 m0, s101, 0x2000
	s_nop 0
	global_load_lds_dwordx4 v206, s[98:99]
	s_add_i32 m0, s101, 0x4000
	s_mov_b64 s[4:5], 0
	global_load_lds_dwordx4 v206, s[28:29]
	s_add_u32 s98, s28, s86
	s_addc_u32 s99, s29, s87
	s_add_i32 m0, s101, 0x6000
	s_nop 0
	global_load_lds_dwordx4 v206, s[98:99]
.LBB0_605:
	s_andn2_b64 vcc, exec, s[4:5]
	s_cbranch_vccnz .LBB0_607
	s_mul_i32 s5, s9, 0x3000
	s_mul_hi_i32 s4, s9, 0x3000
	s_add_u32 s28, s61, s5
	s_addc_u32 s29, s3, s4
	s_add_u32 s4, s28, s19
	s_addc_u32 s5, s29, 0
	s_add_u32 s28, s28, s20
	s_addc_u32 s29, s29, 0
	s_add_i32 s101, s8, s60
	s_mov_b32 m0, s101
	s_nop 0
	global_load_lds_dwordx4 v206, s[4:5]
	s_add_u32 s98, s4, s86
	s_addc_u32 s99, s5, s87
	s_add_i32 m0, s101, 0x2000
	s_nop 0
	global_load_lds_dwordx4 v206, s[98:99]
	s_add_i32 m0, s101, 0x4000
	s_nop 0
	global_load_lds_dwordx4 v206, s[28:29]
	s_add_u32 s98, s28, s86
	s_addc_u32 s99, s29, s87
	s_add_i32 m0, s101, 0x6000
	s_nop 0
	global_load_lds_dwordx4 v206, s[98:99]

.LBB0_608:
	s_andn2_b64 vcc, exec, s[4:5]
	s_cbranch_vccnz .LBB0_610
	s_ashr_i32 s29, s26, 31
	s_add_u32 s4, s64, s26
	s_addc_u32 s5, s65, s29
	s_add_u32 s28, s80, s26
	s_addc_u32 s29, s81, s29
	s_add_i32 s101, s8, s60
	s_mov_b32 m0, s101
	s_nop 0
	global_load_lds_dwordx4 v162, s[4:5]
	s_add_u32 s98, s4, s34
	s_addc_u32 s99, s5, s35
	s_add_i32 m0, s101, 0x2000
	s_nop 0
	global_load_lds_dwordx4 v162, s[98:99]
	s_add_i32 m0, s101, 0x4000
	s_nop 0
	global_load_lds_dwordx4 v162, s[28:29]
	s_add_u32 s98, s28, s34
	s_addc_u32 s99, s29, s35
	s_add_i32 m0, s101, 0x6000
	s_nop 0
	global_load_lds_dwordx4 v162, s[98:99]
.LBB0_610:
	s_add_i32 s8, s23, 1
	s_cmp_lt_i32 s23, s6
	s_cselect_b64 s[4:5], -1, 0
	s_cmp_lt_i32 s8, s12
	s_cselect_b64 s[28:29], -1, 0
	s_and_b64 s[4:5], s[4:5], s[28:29]
	s_sub_i32 s7, s7, 64
	s_sub_i32 s9, s9, 64
	s_addk_i32 s26, 0x4000
	s_add_i32 s27, s27, 0x8000
	s_and_b64 vcc, exec, s[4:5]
	s_cbranch_vccnz .LBB0_602
	s_branch .LBB0_612

; #define LAS __attribute__((address_space(3)))
; DI void glds16(const char* g, LAS unsigned char* l) { __builtin_amdgcn_global_load_lds((const unsigned*)g, (LAS unsigned*)l, 16, 0, 0); }
; DI void dma_kv128(LAS unsigned char* stage, unsigned ldsw, const char* K, const char* V, unsigned voff, long ldb) {
;   glds16(K + (size_t)voff, stage + ldsw); glds16(K + 32 * ldb + (size_t)voff, stage + ldsw + 8192);
;   glds16(V + (size_t)voff, stage + 16384 + ldsw); glds16(V + 32 * ldb + (size_t)voff, stage + 16384 + ldsw + 8192);
; }
.LBB0_628:
	s_cmp_ge_i32 s8, s14
	s_cbranch_scc0 .LBB0_630
	s_mul_i32 s5, s25, 0x3000
	s_mul_hi_i32 s4, s25, 0x3000
	s_add_u32 s29, s61, s5
	s_addc_u32 s40, s3, s4
	s_add_u32 s4, s29, s17
	s_addc_u32 s5, s40, 0
	s_add_u32 s42, s29, s18
	s_addc_u32 s43, s40, 0
	s_add_i32 s101, s23, s60
	s_mov_b32 m0, s101
	s_nop 0
	global_load_lds_dwordx4 v206, s[4:5]
	s_add_u32 s98, s4, s86
	s_addc_u32 s99, s5, s87
	s_add_i32 m0, s101, 0x2000
	s_nop 0
	global_load_lds_dwordx4 v206, s[98:99]
	s_add_i32 m0, s101, 0x4000
	s_mov_b64 s[4:5], 0
	global_load_lds_dwordx4 v206, s[42:43]
	s_add_u32 s98, s42, s86
	s_addc_u32 s99, s43, s87
	s_add_i32 m0, s101, 0x6000
	s_nop 0
	global_load_lds_dwordx4 v206, s[98:99]
.LBB0_630:
	s_andn2_b64 vcc, exec, s[4:5]
	s_cbranch_vccnz .LBB0_632
	s_mul_i32 s5, s26, 0x3000
	s_mul_hi_i32 s4, s26, 0x3000
	s_add_u32 s29, s61, s5
	s_addc_u32 s40, s3, s4
	s_add_u32 s4, s29, s19
	s_addc_u32 s5, s40, 0
	s_add_u32 s42, s29, s20
	s_addc_u32 s43, s40, 0
	s_add_i32 s101, s23, s60
	s_mov_b32 m0, s101
	s_nop 0
	global_load_lds_dwordx4 v206, s[4:5]
	s_add_u32 s98, s4, s86
	s_addc_u32 s99, s5, s87
	s_add_i32 m0, s101, 0x2000
	s_nop 0
	global_load_lds_dwordx4 v206, s[98:99]
	s_add_i32 m0, s101, 0x4000
	s_nop 0
	global_load_lds_dwordx4 v206, s[42:43]
	s_add_u32 s98, s42, s86
	s_addc_u32 s99, s43, s87
	s_add_i32 m0, s101, 0x6000
	s_nop 0
	global_load_lds_dwordx4 v206, s[98:99]

.LBB0_633:
	s_andn2_b64 vcc, exec, s[4:5]
	s_cbranch_vccnz .LBB0_635
	s_ashr_i32 s29, s27, 31
	s_add_u32 s4, s64, s27
	s_addc_u32 s5, s65, s29
	s_add_u32 s42, s80, s27
	s_addc_u32 s43, s81, s29
	s_add_i32 s101, s23, s60
	s_mov_b32 m0, s101
	s_nop 0
	global_load_lds_dwordx4 v162, s[4:5]
	s_add_u32 s98, s4, s34
	s_addc_u32 s99, s5, s35
	s_add_i32 m0, s101, 0x2000
	s_nop 0
	global_load_lds_dwordx4 v162, s[98:99]
	s_add_i32 m0, s101, 0x4000
	s_nop 0
	global_load_lds_dwordx4 v162, s[42:43]
	s_add_u32 s98, s42, s34
	s_addc_u32 s99, s43, s35
	s_add_i32 m0, s101, 0x6000
	s_nop 0
	global_load_lds_dwordx4 v162, s[98:99]
.LBB0_635:
	s_add_i32 s23, s8, 1
	s_cmp_lt_i32 s8, s24
	s_cselect_b64 s[4:5], -1, 0
	s_cmp_lt_i32 s23, s12
	s_cselect_b64 s[42:43], -1, 0
	s_and_b64 s[4:5], s[4:5], s[42:43]
	s_sub_i32 s25, s25, 64
	s_sub_i32 s26, s26, 64
	s_addk_i32 s27, 0x4000
	s_add_i32 s28, s28, 0x8000
	s_and_b64 vcc, exec, s[4:5]
	s_cbranch_vccnz .LBB0_627
	s_branch .LBB0_637

; #define LAS __attribute__((address_space(3)))
; DI void glds16(const char* g, LAS unsigned char* l) { __builtin_amdgcn_global_load_lds((const unsigned*)g, (LAS unsigned*)l, 16, 0, 0); }
; DI void dma_kv128(LAS unsigned char* stage, unsigned ldsw, const char* K, const char* V, unsigned voff, long ldb) {
;   glds16(K + (size_t)voff, stage + ldsw); glds16(K + 32 * ldb + (size_t)voff, stage + ldsw + 8192);
;   glds16(V + (size_t)voff, stage + 16384 + ldsw); glds16(V + 32 * ldb + (size_t)voff, stage + 16384 + ldsw + 8192);
; }
.LBB0_709:
	s_cmp_ge_i32 s18, s14
	s_cbranch_scc0 .LBB0_711
	s_mul_i32 s1, s21, 0x3000
	s_mul_hi_i32 s0, s21, 0x3000
	s_add_u32 s25, s61, s1
	s_addc_u32 s27, s3, s0
	s_add_u32 s0, s25, s6
	s_addc_u32 s1, s27, 0
	s_add_u32 s26, s25, s7
	s_addc_u32 s27, s27, 0
	s_add_i32 s101, s20, s60
	s_mov_b32 m0, s101
	s_nop 0
	global_load_lds_dwordx4 v206, s[0:1]
	s_add_u32 s98, s0, s86
	s_addc_u32 s99, s1, s87
	s_add_i32 m0, s101, 0x2000
	s_nop 0
	global_load_lds_dwordx4 v206, s[98:99]
	s_add_i32 m0, s101, 0x4000
	s_mov_b64 s[0:1], 0
	global_load_lds_dwordx4 v206, s[26:27]
	s_add_u32 s98, s26, s86
	s_addc_u32 s99, s27, s87
	s_add_i32 m0, s101, 0x6000
	s_nop 0
	global_load_lds_dwordx4 v206, s[98:99]
.LBB0_711:
	s_andn2_b64 vcc, exec, s[0:1]
	s_cbranch_vccnz .LBB0_713
	s_mul_i32 s1, s22, 0x3000
	s_mul_hi_i32 s0, s22, 0x3000
	s_add_u32 s25, s61, s1
	s_addc_u32 s27, s3, s0
	s_add_u32 s0, s25, s8
	s_addc_u32 s1, s27, 0
	s_add_u32 s26, s25, s9
	s_addc_u32 s27, s27, 0
	s_add_i32 s101, s20, s60
	s_mov_b32 m0, s101
	s_nop 0
	global_load_lds_dwordx4 v206, s[0:1]
	s_add_u32 s98, s0, s86
	s_addc_u32 s99, s1, s87
	s_add_i32 m0, s101, 0x2000
	s_nop 0
	global_load_lds_dwordx4 v206, s[98:99]
	s_add_i32 m0, s101, 0x4000
	s_nop 0
	global_load_lds_dwordx4 v206, s[26:27]
	s_add_u32 s98, s26, s86
	s_addc_u32 s99, s27, s87
	s_add_i32 m0, s101, 0x6000
	s_nop 0
	global_load_lds_dwordx4 v206, s[98:99]

.LBB0_714:
	s_andn2_b64 vcc, exec, s[0:1]
	s_cbranch_vccnz .LBB0_716
	s_ashr_i32 s25, s23, 31
	s_add_u32 s0, s64, s23
	s_addc_u32 s1, s65, s25
	s_add_u32 s26, s80, s23
	s_addc_u32 s27, s81, s25
	s_add_i32 s101, s20, s60
	s_mov_b32 m0, s101
	s_nop 0
	global_load_lds_dwordx4 v162, s[0:1]
	s_add_u32 s98, s0, s34
	s_addc_u32 s99, s1, s35
	s_add_i32 m0, s101, 0x2000
	s_nop 0
	global_load_lds_dwordx4 v162, s[98:99]
	s_add_i32 m0, s101, 0x4000
	s_nop 0
	global_load_lds_dwordx4 v162, s[26:27]
	s_add_u32 s98, s26, s34
	s_addc_u32 s99, s27, s35
	s_add_i32 m0, s101, 0x6000
	s_nop 0
	global_load_lds_dwordx4 v162, s[98:99]
.LBB0_716:
	s_add_i32 s20, s18, 1
	s_cmp_lt_i32 s18, s17
	s_cselect_b64 s[0:1], -1, 0
	s_cmp_lt_i32 s20, s12
	s_cselect_b64 s[26:27], -1, 0
	s_and_b64 s[0:1], s[0:1], s[26:27]
	s_sub_i32 s21, s21, 64
	s_sub_i32 s22, s22, 64
	s_addk_i32 s23, 0x4000
	s_add_i32 s24, s24, 0x8000
	s_and_b64 vcc, exec, s[0:1]
	s_cbranch_vccnz .LBB0_708
	s_branch .LBB0_718

; #define LAS __attribute__((address_space(3)))
; DI void glds16(const char* g, LAS unsigned char* l) { __builtin_amdgcn_global_load_lds((const unsigned*)g, (LAS unsigned*)l, 16, 0, 0); }
; DI void dma_kv128(LAS unsigned char* stage, unsigned ldsw, const char* K, const char* V, unsigned voff, long ldb) {
;   glds16(K + (size_t)voff, stage + ldsw); glds16(K + 32 * ldb + (size_t)voff, stage + ldsw + 8192);
;   glds16(V + (size_t)voff, stage + 16384 + ldsw); glds16(V + 32 * ldb + (size_t)voff, stage + 16384 + ldsw + 8192);
; }
.LBB0_734:
	s_cmp_ge_i32 s20, s14
	s_cbranch_scc0 .LBB0_736
	s_mul_i32 s1, s23, 0x3000
	s_mul_hi_i32 s0, s23, 0x3000
	s_add_u32 s27, s61, s1
	s_addc_u32 s29, s3, s0
	s_add_u32 s0, s27, s6
	s_addc_u32 s1, s29, 0
	s_add_u32 s28, s27, s7
	s_addc_u32 s29, s29, 0
	s_add_i32 s101, s18, s60
	s_mov_b32 m0, s101
	s_nop 0
	global_load_lds_dwordx4 v206, s[0:1]
	s_add_u32 s98, s0, s86
	s_addc_u32 s99, s1, s87
	s_add_i32 m0, s101, 0x2000
	s_nop 0
	global_load_lds_dwordx4 v206, s[98:99]
	s_add_i32 m0, s101, 0x4000
	s_mov_b64 s[0:1], 0
	global_load_lds_dwordx4 v206, s[28:29]
	s_add_u32 s98, s28, s86
	s_addc_u32 s99, s29, s87
	s_add_i32 m0, s101, 0x6000
	s_nop 0
	global_load_lds_dwordx4 v206, s[98:99]
.LBB0_736:
	s_andn2_b64 vcc, exec, s[0:1]
	s_cbranch_vccnz .LBB0_738
	s_mul_i32 s1, s24, 0x3000
	s_mul_hi_i32 s0, s24, 0x3000
	s_add_u32 s27, s61, s1
	s_addc_u32 s29, s3, s0
	s_add_u32 s0, s27, s8
	s_addc_u32 s1, s29, 0
	s_add_u32 s28, s27, s9
	s_addc_u32 s29, s29, 0
	s_add_i32 s101, s18, s60
	s_mov_b32 m0, s101
	s_nop 0
	global_load_lds_dwordx4 v206, s[0:1]
	s_add_u32 s98, s0, s86
	s_addc_u32 s99, s1, s87
	s_add_i32 m0, s101, 0x2000
	s_nop 0
	global_load_lds_dwordx4 v206, s[98:99]
	s_add_i32 m0, s101, 0x4000
	s_nop 0
	global_load_lds_dwordx4 v206, s[28:29]
	s_add_u32 s98, s28, s86
	s_addc_u32 s99, s29, s87
	s_add_i32 m0, s101, 0x6000
	s_nop 0
	global_load_lds_dwordx4 v206, s[98:99]

.LBB0_739:
	s_andn2_b64 vcc, exec, s[0:1]
	s_cbranch_vccnz .LBB0_741
	s_ashr_i32 s27, s25, 31
	s_add_u32 s0, s64, s25
	s_addc_u32 s1, s65, s27
	s_add_u32 s28, s80, s25
	s_addc_u32 s29, s81, s27
	s_add_i32 s101, s18, s60
	s_mov_b32 m0, s101
	s_nop 0
	global_load_lds_dwordx4 v162, s[0:1]
	s_add_u32 s98, s0, s34
	s_addc_u32 s99, s1, s35
	s_add_i32 m0, s101, 0x2000
	s_nop 0
	global_load_lds_dwordx4 v162, s[98:99]
	s_add_i32 m0, s101, 0x4000
	s_nop 0
	global_load_lds_dwordx4 v162, s[28:29]
	s_add_u32 s98, s28, s34
	s_addc_u32 s99, s29, s35
	s_add_i32 m0, s101, 0x6000
	s_nop 0
	global_load_lds_dwordx4 v162, s[98:99]
.LBB0_741:
	s_add_i32 s18, s20, 1
	s_cmp_lt_i32 s20, s22
	s_cselect_b64 s[0:1], -1, 0
	s_cmp_lt_i32 s18, s12
	s_cselect_b64 s[28:29], -1, 0
	s_and_b64 s[0:1], s[0:1], s[28:29]
	s_sub_i32 s23, s23, 64
	s_sub_i32 s24, s24, 64
	s_addk_i32 s25, 0x4000
	s_add_i32 s26, s26, 0x8000
	s_and_b64 vcc, exec, s[0:1]
	s_cbranch_vccnz .LBB0_733
	s_branch .LBB0_743
